# grid barrier: L1 acquire invalidate issued at arrival instead of after the release (on v58)
# speedup vs baseline: 1.0082x; 1.0025x over previous
; #define LAS __attribute__((address_space(3)))
; __device__ __forceinline__ int lane_id_() { int l; asm volatile("v_mbcnt_lo_u32_b32 %0, -1, 0\n\tv_mbcnt_hi_u32_b32 %0, -1, %0" : "=v"(l)); return l; }
; __device__ __forceinline__ unsigned xb_add(unsigned* p, unsigned v) { return __hip_atomic_fetch_add(p, v, __ATOMIC_RELAXED, __HIP_MEMORY_SCOPE_AGENT); }
; __device__ __forceinline__ unsigned xb_xcc_id() { return (unsigned)__builtin_amdgcn_s_getreg((3 << 11) | 20) & 0xFu; }
; __device__ __forceinline__ void grid_bar(const Ctx& F, unsigned) {
;     ...
;     if (F.wid == 0) {
;         if (lane_id_() == 0) {
;             unsigned* bar = (unsigned*)(F.ws + WS_BAR);
;             volatile LAS unsigned* st = (volatile LAS unsigned*)(F.lds + LDS_BYTES - 64);
;             const unsigned x = xb_xcc_id();
;             __builtin_amdgcn_s_waitcnt(0);
;             unsigned nloc = st[0], nx = st[1];
;             if (nloc == 0u) { xcd_barrier_complete(bar, x, nloc, nx); st[0] = nloc; st[1] = nx; }
;             const unsigned old = xb_add(&bar[XB_XSUB(x)], 1u);
.LBB0_184:
	s_lshl_b32 s0, s0, 8
	s_mov_b64 s[10:11], exec
	s_add_u32 s0, s46, s0
	s_addc_u32 s1, s47, 0
	v_mbcnt_lo_u32_b32 v1, s10, 0
	s_add_u32 s8, s0, 0x300000
	v_mbcnt_hi_u32_b32 v1, s11, v1
	s_addc_u32 s9, s1, 0
	v_cmp_eq_u32_e32 vcc, 0, v1
	s_and_saveexec_b64 s[12:13], vcc
	s_cbranch_execz .LBB0_186
	s_bcnt1_i32_b64 s0, s[10:11]
	v_mov_b32_e32 v3, 0x1000
	v_mov_b32_e32 v4, s0
	global_atomic_add v3, v3, v4, s[8:9] offset:1024 sc0
	buffer_inv sc1

; __device__ __forceinline__ unsigned xb_ld(unsigned* p)              { return __hip_atomic_load(p, __ATOMIC_RELAXED, __HIP_MEMORY_SCOPE_AGENT); }
; #define XB_SPIN(cond, bar) do { unsigned _sp = 0; while (cond) { __builtin_amdgcn_s_sleep(1); \
;     if ((++_sp & 255u) == 0u) { if (xb_ld(&(bar)[XB_TMO])) break; if (_sp > XB_SPIN_CAP) { atomicAdd(&(bar)[XB_TMO], 1u); break; } } } } while (0)
; __device__ __forceinline__ void grid_bar(const Ctx& F, unsigned) {
;     ...
;             } else {
;                 XB_SPIN(xb_ld(&bar[XB_XGEN(x)]) == gen, bar);
;                 __builtin_amdgcn_fence(__ATOMIC_ACQUIRE, "agent");
;                 asm volatile("s_waitcnt vmcnt(0)" ::: "memory");
.LBB0_199:
	s_or_b64 exec, exec, s[12:13]
	s_waitcnt vmcnt(0)
	s_waitcnt vmcnt(0)

; __device__ __forceinline__ unsigned xb_ld(unsigned* p)              { return __hip_atomic_load(p, __ATOMIC_RELAXED, __HIP_MEMORY_SCOPE_AGENT); }
; __device__ __forceinline__ unsigned xb_add(unsigned* p, unsigned v) { return __hip_atomic_fetch_add(p, v, __ATOMIC_RELAXED, __HIP_MEMORY_SCOPE_AGENT); }
; #define XB_SPIN(cond, bar) do { unsigned _sp = 0; while (cond) { __builtin_amdgcn_s_sleep(1); \
;     if ((++_sp & 255u) == 0u) { if (xb_ld(&(bar)[XB_TMO])) break; if (_sp > XB_SPIN_CAP) { atomicAdd(&(bar)[XB_TMO], 1u); break; } } } } while (0)
; __device__ __forceinline__ void grid_bar(const Ctx& F, unsigned) {
;     ...
;             if (old + 1u == (gen + 1u) * nloc) {
;                 __builtin_amdgcn_fence(__ATOMIC_RELEASE, "agent");
;                 asm volatile("s_waitcnt vmcnt(0)" ::: "memory");
;                 const unsigned og = xb_add(&bar[XB_TOP], 1u);
;                 const unsigned tg = og / nx;
;                 if (og + 1u == (tg + 1u) * nx) xb_add(&bar[XB_TOPGEN], 1u);
;                 else XB_SPIN(xb_ld(&bar[XB_TOPGEN]) == tg, bar);
;                 __builtin_amdgcn_fence(__ATOMIC_ACQUIRE, "agent");
;                 xb_add(&bar[XB_XGEN(x)], 1u);
.LBB0_217:
	s_or_b64 exec, exec, s[6:7]
	s_mov_b64 s[6:7], exec
	v_mbcnt_lo_u32_b32 v0, s6, 0
	v_mbcnt_hi_u32_b32 v0, s7, v0
	v_cmp_eq_u32_e32 vcc, 0, v0
	s_waitcnt vmcnt(0)
	s_and_saveexec_b64 s[10:11], vcc
	s_cbranch_execz .LBB0_219
	s_bcnt1_i32_b64 s0, s[6:7]
	v_mov_b32_e32 v0, 0x2000
	v_mov_b32_e32 v1, s0
	global_atomic_add v0, v1, s[8:9] offset:1024

; #define LAS __attribute__((address_space(3)))
; __device__ __forceinline__ int lane_id_() { int l; asm volatile("v_mbcnt_lo_u32_b32 %0, -1, 0\n\tv_mbcnt_hi_u32_b32 %0, -1, %0" : "=v"(l)); return l; }
; __device__ __forceinline__ unsigned xb_add(unsigned* p, unsigned v) { return __hip_atomic_fetch_add(p, v, __ATOMIC_RELAXED, __HIP_MEMORY_SCOPE_AGENT); }
; __device__ __forceinline__ unsigned xb_xcc_id() { return (unsigned)__builtin_amdgcn_s_getreg((3 << 11) | 20) & 0xFu; }
; __device__ __forceinline__ void grid_bar(const Ctx& F, unsigned) {
;     ...
;     if (F.wid == 0) {
;         if (lane_id_() == 0) {
;             unsigned* bar = (unsigned*)(F.ws + WS_BAR);
;             volatile LAS unsigned* st = (volatile LAS unsigned*)(F.lds + LDS_BYTES - 64);
;             const unsigned x = xb_xcc_id();
;             __builtin_amdgcn_s_waitcnt(0);
;             unsigned nloc = st[0], nx = st[1];
;             if (nloc == 0u) { xcd_barrier_complete(bar, x, nloc, nx); st[0] = nloc; st[1] = nx; }
;             const unsigned old = xb_add(&bar[XB_XSUB(x)], 1u);
.LBB0_1782:
	s_lshl_b32 s4, s33, 8
	s_mov_b64 s[6:7], exec
	s_add_u32 s4, s46, s4
	s_addc_u32 s5, s47, 0
	v_mbcnt_lo_u32_b32 v1, s6, 0
	s_add_u32 s4, s4, 0x300000
	v_mbcnt_hi_u32_b32 v1, s7, v1
	s_addc_u32 s5, s5, 0
	v_cmp_eq_u32_e32 vcc, 0, v1
	s_and_saveexec_b64 s[8:9], vcc
	s_cbranch_execz .LBB0_1784
	s_bcnt1_i32_b64 s6, s[6:7]
	v_mov_b32_e32 v3, 0x1000
	v_mov_b32_e32 v4, s6
	global_atomic_add v3, v3, v4, s[4:5] offset:1024 sc0
	buffer_inv sc1

; __device__ __forceinline__ unsigned xb_ld(unsigned* p)              { return __hip_atomic_load(p, __ATOMIC_RELAXED, __HIP_MEMORY_SCOPE_AGENT); }
; #define XB_SPIN(cond, bar) do { unsigned _sp = 0; while (cond) { __builtin_amdgcn_s_sleep(1); \
;     if ((++_sp & 255u) == 0u) { if (xb_ld(&(bar)[XB_TMO])) break; if (_sp > XB_SPIN_CAP) { atomicAdd(&(bar)[XB_TMO], 1u); break; } } } } while (0)
; __device__ __forceinline__ void grid_bar(const Ctx& F, unsigned) {
;     ...
;             } else {
;                 XB_SPIN(xb_ld(&bar[XB_XGEN(x)]) == gen, bar);
;                 __builtin_amdgcn_fence(__ATOMIC_ACQUIRE, "agent");
;                 asm volatile("s_waitcnt vmcnt(0)" ::: "memory");
.LBB0_1797:
	s_or_b64 exec, exec, s[8:9]
	s_waitcnt vmcnt(0)
	s_waitcnt vmcnt(0)

; __device__ __forceinline__ unsigned xb_ld(unsigned* p)              { return __hip_atomic_load(p, __ATOMIC_RELAXED, __HIP_MEMORY_SCOPE_AGENT); }
; __device__ __forceinline__ unsigned xb_add(unsigned* p, unsigned v) { return __hip_atomic_fetch_add(p, v, __ATOMIC_RELAXED, __HIP_MEMORY_SCOPE_AGENT); }
; #define XB_SPIN(cond, bar) do { unsigned _sp = 0; while (cond) { __builtin_amdgcn_s_sleep(1); \
;     if ((++_sp & 255u) == 0u) { if (xb_ld(&(bar)[XB_TMO])) break; if (_sp > XB_SPIN_CAP) { atomicAdd(&(bar)[XB_TMO], 1u); break; } } } } while (0)
; __device__ __forceinline__ void grid_bar(const Ctx& F, unsigned) {
;     ...
;             if (old + 1u == (gen + 1u) * nloc) {
;                 __builtin_amdgcn_fence(__ATOMIC_RELEASE, "agent");
;                 asm volatile("s_waitcnt vmcnt(0)" ::: "memory");
;                 const unsigned og = xb_add(&bar[XB_TOP], 1u);
;                 const unsigned tg = og / nx;
;                 if (og + 1u == (tg + 1u) * nx) xb_add(&bar[XB_TOPGEN], 1u);
;                 else XB_SPIN(xb_ld(&bar[XB_TOPGEN]) == tg, bar);
;                 __builtin_amdgcn_fence(__ATOMIC_ACQUIRE, "agent");
;                 xb_add(&bar[XB_XGEN(x)], 1u);
.LBB0_1815:
	s_or_b64 exec, exec, s[2:3]
	s_mov_b64 s[2:3], exec
	v_mbcnt_lo_u32_b32 v0, s2, 0
	v_mbcnt_hi_u32_b32 v0, s3, v0
	v_cmp_eq_u32_e32 vcc, 0, v0
	s_waitcnt vmcnt(0)
	s_and_saveexec_b64 s[6:7], vcc
	s_cbranch_execz .LBB0_1817
	s_bcnt1_i32_b64 s2, s[2:3]
	v_mov_b32_e32 v0, 0x2000
	v_mov_b32_e32 v1, s2
	global_atomic_add v0, v1, s[4:5] offset:1024
